# C tile loop: barrier-variant selection by two scalar compares (hipcc mask-flag glue removed), common variant falls through
# speedup vs baseline: 1.0031x; 1.0031x over previous
.LBB0_341:
	s_cmp_eq_u32 s35, 0
	s_cselect_b64 s[18:19], -1, 0
	s_cbranch_scc1 .Lcg1_w0
	s_cmp_ge_u32 s35, s24
	s_cbranch_scc1 .Lcg1_w0
	s_and_b64 vcc, exec, s[0:1]
	s_cbranch_vccz .Lcg1_w3
	s_waitcnt vmcnt(2) lgkmcnt(0)
	s_barrier

.Lcg1_w3:
	s_waitcnt vmcnt(3) lgkmcnt(0)
	s_barrier
	s_branch .LBB0_348
.Lcg1_w0:
	s_waitcnt vmcnt(0) lgkmcnt(0)
	s_barrier
	s_branch .LBB0_348
